# SwiGLU phases: epilogue alignment barriers removed except for the last unit (leading half's epilogue overlaps the trailing half's last MFMA block)
# speedup vs baseline: 1.0010x; 1.0010x over previous
.LBB0_278:
	ds_read_b128 v[152:155], v149
	ds_read_b128 v[156:159], v149 offset:1024
	ds_read_b128 v[160:163], v149 offset:2048
	ds_read_b128 v[164:167], v149 offset:3072
	ds_read_b128 v[168:171], v150
	ds_read_b128 v[172:175], v150 offset:1024
	ds_read_b128 v[176:179], v150 offset:2048
	ds_read_b128 v[180:183], v150 offset:3072
	s_add_u32 s24, s22, 0xfffc0080
	s_addc_u32 s25, s23, -1
	s_cmp_eq_u32 s50, 12
	s_cselect_b32 s27, s15, s25
	s_cselect_b32 s26, s46, s24
	s_cselect_b32 s25, s13, s49
	s_cselect_b32 s24, s47, s48
	v_lshl_add_u64 v[144:145], s[22:23], 0, v[136:137]
	s_add_i32 m0, s21, 0xc000
	ds_read_b128 v[184:187], v151
	ds_read_b128 v[188:191], v151 offset:1024
	ds_read_b128 v[192:195], v151 offset:2048
	ds_read_b128 v[196:199], v151 offset:3072
	ds_read_b128 v[200:203], v151 offset:4096
	ds_read_b128 v[204:207], v151 offset:5120
	ds_read_b128 v[208:211], v151 offset:6144
	ds_read_b128 v[212:215], v151 offset:7168
	global_load_lds_dwordx4 v[144:145], off
	v_lshl_add_u64 v[144:145], s[22:23], 0, v[138:139]
	s_add_i32 m0, s21, 0xe000
	s_nop 0
	global_load_lds_dwordx4 v[144:145], off
	s_waitcnt vmcnt(8)
	s_waitcnt lgkmcnt(0)
	s_barrier
	s_setprio 1
	s_waitcnt lgkmcnt(0)
	v_mfma_f32_16x16x32_bf16 v[124:127], v[152:155], v[184:187], v[124:127]
	v_mfma_f32_16x16x32_bf16 v[120:123], v[160:163], v[184:187], v[120:123]
	v_mfma_f32_16x16x32_bf16 v[108:111], v[152:155], v[192:195], v[108:111]
	v_mfma_f32_16x16x32_bf16 v[104:107], v[160:163], v[192:195], v[104:107]
	v_mfma_f32_16x16x32_bf16 v[92:95], v[152:155], v[200:203], v[92:95]
	v_mfma_f32_16x16x32_bf16 v[88:91], v[160:163], v[200:203], v[88:91]
	v_mfma_f32_16x16x32_bf16 v[76:79], v[152:155], v[208:211], v[76:79]
	v_mfma_f32_16x16x32_bf16 v[72:75], v[160:163], v[208:211], v[72:75]
	v_mfma_f32_16x16x32_bf16 v[124:127], v[156:159], v[188:191], v[124:127]
	v_mfma_f32_16x16x32_bf16 v[120:123], v[164:167], v[188:191], v[120:123]
	v_mfma_f32_16x16x32_bf16 v[108:111], v[156:159], v[196:199], v[108:111]
	v_mfma_f32_16x16x32_bf16 v[104:107], v[164:167], v[196:199], v[104:107]
	v_mfma_f32_16x16x32_bf16 v[92:95], v[156:159], v[204:207], v[92:95]
	v_mfma_f32_16x16x32_bf16 v[88:91], v[164:167], v[204:207], v[88:91]
	v_mfma_f32_16x16x32_bf16 v[76:79], v[156:159], v[212:215], v[76:79]
	v_mfma_f32_16x16x32_bf16 v[72:75], v[164:167], v[212:215], v[72:75]
	s_setprio 0
	s_setprio 1
	v_mfma_f32_16x16x32_bf16 v[116:119], v[168:171], v[184:187], v[116:119]
	v_mfma_f32_16x16x32_bf16 v[112:115], v[176:179], v[184:187], v[112:115]
	v_mfma_f32_16x16x32_bf16 v[100:103], v[168:171], v[192:195], v[100:103]
	v_mfma_f32_16x16x32_bf16 v[96:99], v[176:179], v[192:195], v[96:99]
	v_mfma_f32_16x16x32_bf16 v[84:87], v[168:171], v[200:203], v[84:87]
	v_mfma_f32_16x16x32_bf16 v[80:83], v[176:179], v[200:203], v[80:83]
	v_mfma_f32_16x16x32_bf16 v[68:71], v[168:171], v[208:211], v[68:71]
	v_mfma_f32_16x16x32_bf16 v[64:67], v[176:179], v[208:211], v[64:67]
	v_mfma_f32_16x16x32_bf16 v[116:119], v[172:175], v[188:191], v[116:119]
	v_mfma_f32_16x16x32_bf16 v[112:115], v[180:183], v[188:191], v[112:115]
	v_mfma_f32_16x16x32_bf16 v[100:103], v[172:175], v[196:199], v[100:103]
	v_mfma_f32_16x16x32_bf16 v[96:99], v[180:183], v[196:199], v[96:99]
	v_mfma_f32_16x16x32_bf16 v[84:87], v[172:175], v[204:207], v[84:87]
	v_mfma_f32_16x16x32_bf16 v[80:83], v[180:183], v[204:207], v[80:83]
	v_mfma_f32_16x16x32_bf16 v[68:71], v[172:175], v[212:215], v[68:71]
	v_mfma_f32_16x16x32_bf16 v[64:67], v[180:183], v[212:215], v[64:67]
	s_setprio 0
	s_barrier
	s_add_i32 s51, s43, s31
	v_lshl_add_u64 v[144:145], s[24:25], 0, v[132:133]
	s_mov_b32 m0, s51
	ds_read_b128 v[184:187], v151 offset:16384
	ds_read_b128 v[188:191], v151 offset:17408
	ds_read_b128 v[192:195], v151 offset:18432
	ds_read_b128 v[196:199], v151 offset:19456
	ds_read_b128 v[200:203], v151 offset:20480
	ds_read_b128 v[204:207], v151 offset:21504
	ds_read_b128 v[208:211], v151 offset:22528
	ds_read_b128 v[212:215], v151 offset:23552
	global_load_lds_dwordx4 v[144:145], off
	s_add_i32 m0, s51, 0x2000
	s_add_u32 s52, s24, 0x40000
	v_lshl_add_u64 v[216:217], s[24:25], 0, v[128:129]
	s_addc_u32 s53, s25, 0
	s_add_i32 s51, s44, s31
	global_load_lds_dwordx4 v[216:217], off
	v_lshl_add_u64 v[218:219], s[52:53], 0, v[132:133]
	s_mov_b32 m0, s51
	v_lshl_add_u64 v[222:223], s[26:27], 0, v[130:131]
	global_load_lds_dwordx4 v[218:219], off
	v_lshl_add_u64 v[218:219], s[52:53], 0, v[128:129]
	s_add_i32 m0, s51, 0x2000
	s_nop 0
	global_load_lds_dwordx4 v[218:219], off
	v_lshl_add_u64 v[218:219], s[26:27], 0, v[134:135]
	s_mov_b32 m0, s21
	s_nop 0
	global_load_lds_dwordx4 v[218:219], off
	s_mov_b32 m0, s35
	s_nop 0
	global_load_lds_dwordx4 v[222:223], off
	s_waitcnt vmcnt(8)
	s_waitcnt lgkmcnt(0)
	s_barrier
	s_setprio 1
	s_waitcnt lgkmcnt(0)
	v_mfma_f32_16x16x32_bf16 v[60:63], v[152:155], v[184:187], v[60:63]
	v_mfma_f32_16x16x32_bf16 v[56:59], v[160:163], v[184:187], v[56:59]
	v_mfma_f32_16x16x32_bf16 v[44:47], v[152:155], v[192:195], v[44:47]
	v_mfma_f32_16x16x32_bf16 v[40:43], v[160:163], v[192:195], v[40:43]
	v_mfma_f32_16x16x32_bf16 v[28:31], v[152:155], v[200:203], v[28:31]
	v_mfma_f32_16x16x32_bf16 v[24:27], v[160:163], v[200:203], v[24:27]
	v_mfma_f32_16x16x32_bf16 v[12:15], v[152:155], v[208:211], v[12:15]
	v_mfma_f32_16x16x32_bf16 v[8:11], v[160:163], v[208:211], v[8:11]
	v_mfma_f32_16x16x32_bf16 v[60:63], v[156:159], v[188:191], v[60:63]
	v_mfma_f32_16x16x32_bf16 v[56:59], v[164:167], v[188:191], v[56:59]
	v_mfma_f32_16x16x32_bf16 v[44:47], v[156:159], v[196:199], v[44:47]
	v_mfma_f32_16x16x32_bf16 v[40:43], v[164:167], v[196:199], v[40:43]
	v_mfma_f32_16x16x32_bf16 v[28:31], v[156:159], v[204:207], v[28:31]
	v_mfma_f32_16x16x32_bf16 v[24:27], v[164:167], v[204:207], v[24:27]
	v_mfma_f32_16x16x32_bf16 v[12:15], v[156:159], v[212:215], v[12:15]
	v_mfma_f32_16x16x32_bf16 v[8:11], v[164:167], v[212:215], v[8:11]
	s_setprio 0
	s_setprio 1
	v_mfma_f32_16x16x32_bf16 v[52:55], v[168:171], v[184:187], v[52:55]
	v_mfma_f32_16x16x32_bf16 v[48:51], v[176:179], v[184:187], v[48:51]
	v_mfma_f32_16x16x32_bf16 v[36:39], v[168:171], v[192:195], v[36:39]
	v_mfma_f32_16x16x32_bf16 v[32:35], v[176:179], v[192:195], v[32:35]
	v_mfma_f32_16x16x32_bf16 v[20:23], v[168:171], v[200:203], v[20:23]
	v_mfma_f32_16x16x32_bf16 v[16:19], v[176:179], v[200:203], v[16:19]
	v_mfma_f32_16x16x32_bf16 v[4:7], v[168:171], v[208:211], v[4:7]
	v_mfma_f32_16x16x32_bf16 v[0:3], v[176:179], v[208:211], v[0:3]
	v_mfma_f32_16x16x32_bf16 v[52:55], v[172:175], v[188:191], v[52:55]
	v_mfma_f32_16x16x32_bf16 v[48:51], v[180:183], v[188:191], v[48:51]
	v_mfma_f32_16x16x32_bf16 v[36:39], v[172:175], v[196:199], v[36:39]
	v_mfma_f32_16x16x32_bf16 v[32:35], v[180:183], v[196:199], v[32:35]
	v_mfma_f32_16x16x32_bf16 v[20:23], v[172:175], v[204:207], v[20:23]
	v_mfma_f32_16x16x32_bf16 v[16:19], v[180:183], v[204:207], v[16:19]
	v_mfma_f32_16x16x32_bf16 v[4:7], v[172:175], v[212:215], v[4:7]
	v_mfma_f32_16x16x32_bf16 v[0:3], v[180:183], v[212:215], v[0:3]
	s_setprio 0
	s_barrier
	s_add_i32 s51, 0, 0x18000
	s_add_i32 s52, 0, 0x1c000
	v_add_u32_e32 v164, s51, v147
	v_add_u32_e32 v180, s52, v147
	ds_read_b128 v[152:155], v164
	ds_read_b128 v[156:159], v164 offset:1024
	ds_read_b128 v[160:163], v164 offset:2048
	ds_read_b128 v[164:167], v164 offset:3072
	ds_read_b128 v[168:171], v180
	ds_read_b128 v[172:175], v180 offset:1024
	ds_read_b128 v[176:179], v180 offset:2048
	ds_read_b128 v[180:183], v180 offset:3072
	s_add_u32 s26, s26, 0x40000
	s_addc_u32 s27, s27, 0
	s_mov_b32 m0, s36
	v_lshl_add_u64 v[224:225], s[26:27], 0, v[134:135]
	ds_read_b128 v[184:187], v151 offset:32768
	ds_read_b128 v[188:191], v151 offset:33792
	ds_read_b128 v[192:195], v151 offset:34816
	ds_read_b128 v[196:199], v151 offset:35840
	ds_read_b128 v[200:203], v151 offset:36864
	ds_read_b128 v[204:207], v151 offset:37888
	ds_read_b128 v[208:211], v151 offset:38912
	ds_read_b128 v[212:215], v151 offset:39936
	global_load_lds_dwordx4 v[224:225], off
	v_lshl_add_u64 v[224:225], s[26:27], 0, v[130:131]
	s_mov_b32 m0, s37
	s_nop 0
	global_load_lds_dwordx4 v[224:225], off
	s_waitcnt vmcnt(8)
	s_waitcnt lgkmcnt(0)
	s_barrier
	s_setprio 1
	s_waitcnt lgkmcnt(0)
	v_mfma_f32_16x16x32_bf16 v[124:127], v[152:155], v[184:187], v[124:127]
	v_mfma_f32_16x16x32_bf16 v[120:123], v[160:163], v[184:187], v[120:123]
	v_mfma_f32_16x16x32_bf16 v[108:111], v[152:155], v[192:195], v[108:111]
	v_mfma_f32_16x16x32_bf16 v[104:107], v[160:163], v[192:195], v[104:107]
	v_mfma_f32_16x16x32_bf16 v[92:95], v[152:155], v[200:203], v[92:95]
	v_mfma_f32_16x16x32_bf16 v[88:91], v[160:163], v[200:203], v[88:91]
	v_mfma_f32_16x16x32_bf16 v[76:79], v[152:155], v[208:211], v[76:79]
	v_mfma_f32_16x16x32_bf16 v[72:75], v[160:163], v[208:211], v[72:75]
	v_mfma_f32_16x16x32_bf16 v[124:127], v[156:159], v[188:191], v[124:127]
	v_mfma_f32_16x16x32_bf16 v[120:123], v[164:167], v[188:191], v[120:123]
	v_mfma_f32_16x16x32_bf16 v[108:111], v[156:159], v[196:199], v[108:111]
	v_mfma_f32_16x16x32_bf16 v[104:107], v[164:167], v[196:199], v[104:107]
	v_mfma_f32_16x16x32_bf16 v[92:95], v[156:159], v[204:207], v[92:95]
	v_mfma_f32_16x16x32_bf16 v[88:91], v[164:167], v[204:207], v[88:91]
	v_mfma_f32_16x16x32_bf16 v[76:79], v[156:159], v[212:215], v[76:79]
	v_mfma_f32_16x16x32_bf16 v[72:75], v[164:167], v[212:215], v[72:75]
	s_setprio 0
	s_setprio 1
	v_mfma_f32_16x16x32_bf16 v[116:119], v[168:171], v[184:187], v[116:119]
	v_mfma_f32_16x16x32_bf16 v[112:115], v[176:179], v[184:187], v[112:115]
	v_mfma_f32_16x16x32_bf16 v[100:103], v[168:171], v[192:195], v[100:103]
	v_mfma_f32_16x16x32_bf16 v[96:99], v[176:179], v[192:195], v[96:99]
	v_mfma_f32_16x16x32_bf16 v[84:87], v[168:171], v[200:203], v[84:87]
	v_mfma_f32_16x16x32_bf16 v[80:83], v[176:179], v[200:203], v[80:83]
	v_mfma_f32_16x16x32_bf16 v[68:71], v[168:171], v[208:211], v[68:71]
	v_mfma_f32_16x16x32_bf16 v[64:67], v[176:179], v[208:211], v[64:67]
	v_mfma_f32_16x16x32_bf16 v[116:119], v[172:175], v[188:191], v[116:119]
	v_mfma_f32_16x16x32_bf16 v[112:115], v[180:183], v[188:191], v[112:115]
	v_mfma_f32_16x16x32_bf16 v[100:103], v[172:175], v[196:199], v[100:103]
	v_mfma_f32_16x16x32_bf16 v[96:99], v[180:183], v[196:199], v[96:99]
	v_mfma_f32_16x16x32_bf16 v[84:87], v[172:175], v[204:207], v[84:87]
	v_mfma_f32_16x16x32_bf16 v[80:83], v[180:183], v[204:207], v[80:83]
	v_mfma_f32_16x16x32_bf16 v[68:71], v[172:175], v[212:215], v[68:71]
	v_mfma_f32_16x16x32_bf16 v[64:67], v[180:183], v[212:215], v[64:67]
	s_setprio 0
	s_barrier
	s_add_i32 s26, s51, s31
	v_lshl_add_u64 v[144:145], v[144:145], 0, s[8:9]
	s_mov_b32 m0, s26
	ds_read_b128 v[184:187], v151 offset:49152
	ds_read_b128 v[188:191], v151 offset:50176
	ds_read_b128 v[192:195], v151 offset:51200
	ds_read_b128 v[196:199], v151 offset:52224
	ds_read_b128 v[200:203], v151 offset:53248
	ds_read_b128 v[204:207], v151 offset:54272
	ds_read_b128 v[208:211], v151 offset:55296
	ds_read_b128 v[212:215], v151 offset:56320
	global_load_lds_dwordx4 v[144:145], off
	s_add_i32 m0, s26, 0x2000
	s_add_u32 s24, s24, 0x40080
	v_lshl_add_u64 v[144:145], v[216:217], 0, s[8:9]
	s_addc_u32 s25, s25, 0
	s_add_i32 s26, s52, s31
	global_load_lds_dwordx4 v[144:145], off
	v_lshl_add_u64 v[144:145], s[24:25], 0, v[132:133]
	s_mov_b32 m0, s26
	s_nop 0
	global_load_lds_dwordx4 v[144:145], off
	v_lshl_add_u64 v[144:145], s[24:25], 0, v[128:129]
	s_add_i32 m0, s26, 0x2000
	s_nop 0
	global_load_lds_dwordx4 v[144:145], off
	v_lshl_add_u64 v[144:145], v[218:219], 0, s[8:9]
	s_mov_b32 m0, s39
	s_nop 0
	global_load_lds_dwordx4 v[144:145], off
	v_lshl_add_u64 v[144:145], v[222:223], 0, s[8:9]
	s_mov_b32 m0, s40
	s_nop 0
	global_load_lds_dwordx4 v[144:145], off
	s_waitcnt vmcnt(8)
	s_waitcnt lgkmcnt(0)
	s_barrier
	s_setprio 1
	s_waitcnt lgkmcnt(0)
	v_mfma_f32_16x16x32_bf16 v[60:63], v[152:155], v[184:187], v[60:63]
	v_mfma_f32_16x16x32_bf16 v[56:59], v[160:163], v[184:187], v[56:59]
	v_mfma_f32_16x16x32_bf16 v[44:47], v[152:155], v[192:195], v[44:47]
	v_mfma_f32_16x16x32_bf16 v[40:43], v[160:163], v[192:195], v[40:43]
	v_mfma_f32_16x16x32_bf16 v[28:31], v[152:155], v[200:203], v[28:31]
	v_mfma_f32_16x16x32_bf16 v[24:27], v[160:163], v[200:203], v[24:27]
	v_mfma_f32_16x16x32_bf16 v[12:15], v[152:155], v[208:211], v[12:15]
	v_mfma_f32_16x16x32_bf16 v[8:11], v[160:163], v[208:211], v[8:11]
	v_mfma_f32_16x16x32_bf16 v[60:63], v[156:159], v[188:191], v[60:63]
	v_mfma_f32_16x16x32_bf16 v[56:59], v[164:167], v[188:191], v[56:59]
	v_mfma_f32_16x16x32_bf16 v[44:47], v[156:159], v[196:199], v[44:47]
	v_mfma_f32_16x16x32_bf16 v[40:43], v[164:167], v[196:199], v[40:43]
	v_mfma_f32_16x16x32_bf16 v[28:31], v[156:159], v[204:207], v[28:31]
	v_mfma_f32_16x16x32_bf16 v[24:27], v[164:167], v[204:207], v[24:27]
	v_mfma_f32_16x16x32_bf16 v[12:15], v[156:159], v[212:215], v[12:15]
	v_mfma_f32_16x16x32_bf16 v[8:11], v[164:167], v[212:215], v[8:11]
	s_setprio 0
	s_setprio 1
	v_mfma_f32_16x16x32_bf16 v[52:55], v[168:171], v[184:187], v[52:55]
	v_mfma_f32_16x16x32_bf16 v[48:51], v[176:179], v[184:187], v[48:51]
	v_mfma_f32_16x16x32_bf16 v[36:39], v[168:171], v[192:195], v[36:39]
	v_mfma_f32_16x16x32_bf16 v[32:35], v[176:179], v[192:195], v[32:35]
	v_mfma_f32_16x16x32_bf16 v[20:23], v[168:171], v[200:203], v[20:23]
	v_mfma_f32_16x16x32_bf16 v[16:19], v[176:179], v[200:203], v[16:19]
	v_mfma_f32_16x16x32_bf16 v[4:7], v[168:171], v[208:211], v[4:7]
	v_mfma_f32_16x16x32_bf16 v[0:3], v[176:179], v[208:211], v[0:3]
	v_mfma_f32_16x16x32_bf16 v[52:55], v[172:175], v[188:191], v[52:55]
	v_mfma_f32_16x16x32_bf16 v[48:51], v[180:183], v[188:191], v[48:51]
	v_mfma_f32_16x16x32_bf16 v[36:39], v[172:175], v[196:199], v[36:39]
	v_mfma_f32_16x16x32_bf16 v[32:35], v[180:183], v[196:199], v[32:35]
	v_mfma_f32_16x16x32_bf16 v[20:23], v[172:175], v[204:207], v[20:23]
	v_mfma_f32_16x16x32_bf16 v[16:19], v[180:183], v[204:207], v[16:19]
	v_mfma_f32_16x16x32_bf16 v[4:7], v[172:175], v[212:215], v[4:7]
	v_mfma_f32_16x16x32_bf16 v[0:3], v[180:183], v[212:215], v[0:3]
	s_setprio 0
	s_barrier
	s_add_i32 s50, s50, 2
	s_add_u32 s22, s22, 0x100
	s_addc_u32 s23, s23, 0
	s_add_u32 s48, s48, 0x100
	s_addc_u32 s49, s49, 0
	s_cmp_gt_u32 s50, 13
	s_cbranch_scc0 .LBB0_278
	s_andn2_b64 vcc, s[10:11], s[4:5]
	s_and_b64 vcc, exec, vcc
	s_cbranch_vccz .LBB0_281
	s_barrier
.LBB0_281:
	v_mul_f32_e32 v144, 0xbfb8aa3b, v124
	v_exp_f32_e32 v144, v144
	v_mul_f32_e32 v145, 0xbfb8aa3b, v125
	v_exp_f32_e32 v145, v145
	v_mul_f32_e32 v153, 0xbfb8aa3b, v126
	v_add_f32_e32 v144, 1.0, v144
	v_rcp_f32_e32 v156, v144
	v_add_f32_e32 v144, 1.0, v145
	v_rcp_f32_e32 v157, v144
	v_exp_f32_e32 v153, v153
	v_lshl_or_b32 v154, s2, 7, v148
	v_lshl_add_u32 v152, s20, 8, v146
	v_pk_mul_f32 v[124:125], v[124:125], v[156:157]
	v_mul_f32_e32 v156, 0xbfb8aa3b, v127
	v_exp_f32_e32 v156, v156
	v_pk_mul_f32 v[116:117], v[124:125], v[116:117]
	v_add_f32_e32 v124, 1.0, v153
	v_mul_f32_e32 v153, 0xbfb8aa3b, v120
	v_add_f32_e32 v125, 1.0, v156
	v_rcp_f32_e32 v124, v124
	v_rcp_f32_e32 v125, v125
	v_exp_f32_e32 v153, v153
	v_mul_f32_e32 v156, 0xbfb8aa3b, v121
	v_exp_f32_e32 v156, v156
	v_pk_mul_f32 v[124:125], v[126:127], v[124:125]
	v_add_f32_e32 v126, 1.0, v153
	v_mul_f32_e32 v153, 0xbfb8aa3b, v122
	v_add_f32_e32 v127, 1.0, v156
	v_exp_f32_e32 v153, v153
	v_mul_f32_e32 v156, 0xbfb8aa3b, v123
	v_exp_f32_e32 v157, v156
	v_rcp_f32_e32 v126, v126
	v_add_f32_e32 v153, 1.0, v153
	v_rcp_f32_e32 v127, v127
	v_rcp_f32_e32 v156, v153
	v_add_f32_e32 v153, 1.0, v157
	v_rcp_f32_e32 v157, v153
	v_pk_mul_f32 v[120:121], v[120:121], v[126:127]
	v_pk_mul_f32 v[118:119], v[124:125], v[118:119]
	v_pk_mul_f32 v[120:121], v[120:121], v[112:113]
	v_pk_mul_f32 v[112:113], v[122:123], v[156:157]
	v_ashrrev_i32_e32 v155, 31, v154
	v_pk_mul_f32 v[122:123], v[112:113], v[114:115]
	v_cvt_pk_bf16_f32 v115, v118, v119
	v_mul_f32_e32 v118, 0xbfb8aa3b, v108
	v_mul_f32_e32 v119, 0xbfb8aa3b, v109
	v_exp_f32_e32 v118, v118
	v_exp_f32_e32 v119, v119
	v_mov_b64_e32 v[144:145], s[6:7]
	v_mad_i64_i32 v[158:159], s[22:23], v152, s45, v[144:145]
	v_lshlrev_b64 v[112:113], 1, v[154:155]
	v_lshl_add_u64 v[124:125], v[158:159], 0, v[112:113]
	v_cvt_pk_bf16_f32 v114, v116, v117
	v_cvt_pk_bf16_f32 v116, v120, v121
	v_cvt_pk_bf16_f32 v117, v122, v123
	global_store_dwordx4 v[124:125], v[114:117], off
	s_andn2_b64 vcc, exec, s[4:5]
	s_mov_b64 s[4:5], -1
	v_add_f32_e32 v114, 1.0, v118
	v_add_f32_e32 v115, 1.0, v119
	v_rcp_f32_e32 v114, v114
	v_rcp_f32_e32 v115, v115
	v_or_b32_e32 v116, 16, v152
	v_mad_i64_i32 v[116:117], s[22:23], v116, s45, v[144:145]
	v_pk_mul_f32 v[108:109], v[108:109], v[114:115]
	v_mul_f32_e32 v114, 0xbfb8aa3b, v110
	v_mul_f32_e32 v115, 0xbfb8aa3b, v111
	v_exp_f32_e32 v114, v114
	v_exp_f32_e32 v115, v115
	v_pk_mul_f32 v[100:101], v[108:109], v[100:101]
	v_add_f32_e32 v108, 1.0, v114
	v_add_f32_e32 v109, 1.0, v115
	v_mul_f32_e32 v114, 0xbfb8aa3b, v104
	v_mul_f32_e32 v115, 0xbfb8aa3b, v105
	v_rcp_f32_e32 v108, v108
	v_rcp_f32_e32 v109, v109
	v_exp_f32_e32 v114, v114
	v_exp_f32_e32 v115, v115
	v_pk_mul_f32 v[108:109], v[110:111], v[108:109]
	v_add_f32_e32 v110, 1.0, v114
	v_add_f32_e32 v111, 1.0, v115
	v_mul_f32_e32 v114, 0xbfb8aa3b, v106
	v_mul_f32_e32 v115, 0xbfb8aa3b, v107
	v_exp_f32_e32 v114, v114
	v_exp_f32_e32 v115, v115
	v_rcp_f32_e32 v110, v110
	v_rcp_f32_e32 v111, v111
	v_add_f32_e32 v114, 1.0, v114
	v_add_f32_e32 v115, 1.0, v115
	v_rcp_f32_e32 v114, v114
	v_rcp_f32_e32 v115, v115
	v_pk_mul_f32 v[104:105], v[104:105], v[110:111]
	v_pk_mul_f32 v[102:103], v[108:109], v[102:103]
	v_pk_mul_f32 v[104:105], v[104:105], v[96:97]
	v_pk_mul_f32 v[96:97], v[106:107], v[114:115]
	v_lshl_add_u64 v[108:109], v[116:117], 0, v[112:113]
	v_pk_mul_f32 v[106:107], v[96:97], v[98:99]
	v_cvt_pk_bf16_f32 v96, v100, v101
	v_mul_f32_e32 v100, 0xbfb8aa3b, v92
	v_mul_f32_e32 v101, 0xbfb8aa3b, v93
	v_exp_f32_e32 v100, v100
	v_exp_f32_e32 v101, v101
	v_cvt_pk_bf16_f32 v97, v102, v103
	v_cvt_pk_bf16_f32 v98, v104, v105
	v_cvt_pk_bf16_f32 v99, v106, v107
	global_store_dwordx4 v[108:109], v[96:99], off
	s_nop 1
	v_add_f32_e32 v96, 1.0, v100
	v_add_f32_e32 v97, 1.0, v101
	v_rcp_f32_e32 v96, v96
	v_rcp_f32_e32 v97, v97
	v_or_b32_e32 v98, 32, v152
	v_mad_i64_i32 v[98:99], s[22:23], v98, s45, v[144:145]
	v_pk_mul_f32 v[92:93], v[92:93], v[96:97]
	v_mul_f32_e32 v96, 0xbfb8aa3b, v94
	v_mul_f32_e32 v97, 0xbfb8aa3b, v95
	v_exp_f32_e32 v96, v96
	v_exp_f32_e32 v97, v97
	v_pk_mul_f32 v[84:85], v[92:93], v[84:85]
	v_add_f32_e32 v92, 1.0, v96
	v_add_f32_e32 v93, 1.0, v97
	v_mul_f32_e32 v96, 0xbfb8aa3b, v88
	v_mul_f32_e32 v97, 0xbfb8aa3b, v89
	v_rcp_f32_e32 v92, v92
	v_rcp_f32_e32 v93, v93
	v_exp_f32_e32 v96, v96
	v_exp_f32_e32 v97, v97
	v_pk_mul_f32 v[92:93], v[94:95], v[92:93]
	v_add_f32_e32 v94, 1.0, v96
	v_add_f32_e32 v95, 1.0, v97
	v_mul_f32_e32 v96, 0xbfb8aa3b, v90
	v_mul_f32_e32 v97, 0xbfb8aa3b, v91
	v_exp_f32_e32 v96, v96
	v_exp_f32_e32 v97, v97
	v_rcp_f32_e32 v94, v94
	v_rcp_f32_e32 v95, v95
	v_add_f32_e32 v96, 1.0, v96
	v_add_f32_e32 v97, 1.0, v97
	v_rcp_f32_e32 v96, v96
	v_rcp_f32_e32 v97, v97
	v_pk_mul_f32 v[88:89], v[88:89], v[94:95]
	v_pk_mul_f32 v[86:87], v[92:93], v[86:87]
	v_pk_mul_f32 v[88:89], v[88:89], v[80:81]
	v_pk_mul_f32 v[80:81], v[90:91], v[96:97]
	v_lshl_add_u64 v[92:93], v[98:99], 0, v[112:113]
	v_pk_mul_f32 v[90:91], v[80:81], v[82:83]
	v_cvt_pk_bf16_f32 v80, v84, v85
	v_mul_f32_e32 v84, 0xbfb8aa3b, v76
	v_mul_f32_e32 v85, 0xbfb8aa3b, v77
	v_exp_f32_e32 v84, v84
	v_exp_f32_e32 v85, v85
	v_cvt_pk_bf16_f32 v81, v86, v87
	v_cvt_pk_bf16_f32 v82, v88, v89
	v_cvt_pk_bf16_f32 v83, v90, v91
	global_store_dwordx4 v[92:93], v[80:83], off
	s_nop 1
	v_add_f32_e32 v80, 1.0, v84
	v_add_f32_e32 v81, 1.0, v85
	v_rcp_f32_e32 v80, v80
	v_rcp_f32_e32 v81, v81
	v_or_b32_e32 v82, 48, v152
	v_mad_i64_i32 v[82:83], s[22:23], v82, s45, v[144:145]
	v_pk_mul_f32 v[76:77], v[76:77], v[80:81]
	v_mul_f32_e32 v80, 0xbfb8aa3b, v78
	v_mul_f32_e32 v81, 0xbfb8aa3b, v79
	v_exp_f32_e32 v80, v80
	v_exp_f32_e32 v81, v81
	v_pk_mul_f32 v[68:69], v[76:77], v[68:69]
	v_add_f32_e32 v76, 1.0, v80
	v_add_f32_e32 v77, 1.0, v81
	v_mul_f32_e32 v80, 0xbfb8aa3b, v72
	v_mul_f32_e32 v81, 0xbfb8aa3b, v73
	v_rcp_f32_e32 v76, v76
	v_rcp_f32_e32 v77, v77
	v_exp_f32_e32 v80, v80
	v_exp_f32_e32 v81, v81
	v_pk_mul_f32 v[76:77], v[78:79], v[76:77]
	v_add_f32_e32 v78, 1.0, v80
	v_add_f32_e32 v79, 1.0, v81
	v_mul_f32_e32 v80, 0xbfb8aa3b, v74
	v_mul_f32_e32 v81, 0xbfb8aa3b, v75
	v_exp_f32_e32 v80, v80
	v_exp_f32_e32 v81, v81
	v_rcp_f32_e32 v78, v78
	v_rcp_f32_e32 v79, v79
	v_add_f32_e32 v80, 1.0, v80
	v_add_f32_e32 v81, 1.0, v81
	v_rcp_f32_e32 v80, v80
	v_rcp_f32_e32 v81, v81
	v_pk_mul_f32 v[72:73], v[72:73], v[78:79]
	v_pk_mul_f32 v[70:71], v[76:77], v[70:71]
	v_pk_mul_f32 v[72:73], v[72:73], v[64:65]
	v_pk_mul_f32 v[64:65], v[74:75], v[80:81]
	v_lshl_add_u64 v[76:77], v[82:83], 0, v[112:113]
	v_pk_mul_f32 v[74:75], v[64:65], v[66:67]
	v_cvt_pk_bf16_f32 v64, v68, v69
	v_mul_f32_e32 v68, 0xbfb8aa3b, v60
	v_mul_f32_e32 v69, 0xbfb8aa3b, v61
	v_exp_f32_e32 v68, v68
	v_exp_f32_e32 v69, v69
	v_cvt_pk_bf16_f32 v65, v70, v71
	v_cvt_pk_bf16_f32 v66, v72, v73
	v_cvt_pk_bf16_f32 v67, v74, v75
	global_store_dwordx4 v[76:77], v[64:67], off
	s_nop 1
	v_add_f32_e32 v64, 1.0, v68
	v_add_f32_e32 v65, 1.0, v69
	v_rcp_f32_e32 v64, v64
	v_rcp_f32_e32 v65, v65
	v_add_u32_e32 v66, 0x80, v152
	v_mad_i64_i32 v[66:67], s[22:23], v66, s45, v[144:145]
	v_pk_mul_f32 v[60:61], v[60:61], v[64:65]
	v_mul_f32_e32 v64, 0xbfb8aa3b, v62
	v_mul_f32_e32 v65, 0xbfb8aa3b, v63
	v_exp_f32_e32 v64, v64
	v_exp_f32_e32 v65, v65
	v_pk_mul_f32 v[52:53], v[60:61], v[52:53]
	v_add_f32_e32 v60, 1.0, v64
	v_add_f32_e32 v61, 1.0, v65
	v_mul_f32_e32 v64, 0xbfb8aa3b, v56
	v_mul_f32_e32 v65, 0xbfb8aa3b, v57
	v_rcp_f32_e32 v60, v60
	v_rcp_f32_e32 v61, v61
	v_exp_f32_e32 v64, v64
	v_exp_f32_e32 v65, v65
	v_pk_mul_f32 v[60:61], v[62:63], v[60:61]
	v_add_f32_e32 v62, 1.0, v64
	v_add_f32_e32 v63, 1.0, v65
	v_mul_f32_e32 v64, 0xbfb8aa3b, v58
	v_mul_f32_e32 v65, 0xbfb8aa3b, v59
	v_exp_f32_e32 v64, v64
	v_exp_f32_e32 v65, v65
	v_rcp_f32_e32 v62, v62
	v_rcp_f32_e32 v63, v63
	v_add_f32_e32 v64, 1.0, v64
	v_add_f32_e32 v65, 1.0, v65
	v_rcp_f32_e32 v64, v64
	v_rcp_f32_e32 v65, v65
	v_pk_mul_f32 v[56:57], v[56:57], v[62:63]
	v_pk_mul_f32 v[54:55], v[60:61], v[54:55]
	v_pk_mul_f32 v[56:57], v[56:57], v[48:49]
	v_pk_mul_f32 v[48:49], v[58:59], v[64:65]
	v_lshl_add_u64 v[60:61], v[66:67], 0, v[112:113]
	v_pk_mul_f32 v[58:59], v[48:49], v[50:51]
	v_cvt_pk_bf16_f32 v48, v52, v53
	v_mul_f32_e32 v52, 0xbfb8aa3b, v44
	v_mul_f32_e32 v53, 0xbfb8aa3b, v45
	v_exp_f32_e32 v52, v52
	v_exp_f32_e32 v53, v53
	v_cvt_pk_bf16_f32 v49, v54, v55
	v_cvt_pk_bf16_f32 v50, v56, v57
	v_cvt_pk_bf16_f32 v51, v58, v59
	global_store_dwordx4 v[60:61], v[48:51], off
	s_nop 1
	v_add_f32_e32 v48, 1.0, v52
	v_add_f32_e32 v49, 1.0, v53
	v_rcp_f32_e32 v48, v48
	v_rcp_f32_e32 v49, v49
	v_add_u32_e32 v50, 0x90, v152
	v_mad_i64_i32 v[50:51], s[22:23], v50, s45, v[144:145]
	v_pk_mul_f32 v[44:45], v[44:45], v[48:49]
	v_mul_f32_e32 v48, 0xbfb8aa3b, v46
	v_mul_f32_e32 v49, 0xbfb8aa3b, v47
	v_exp_f32_e32 v48, v48
	v_exp_f32_e32 v49, v49
	v_pk_mul_f32 v[36:37], v[44:45], v[36:37]
	v_add_f32_e32 v44, 1.0, v48
	v_add_f32_e32 v45, 1.0, v49
	v_mul_f32_e32 v48, 0xbfb8aa3b, v40
	v_mul_f32_e32 v49, 0xbfb8aa3b, v41
	v_rcp_f32_e32 v44, v44
	v_rcp_f32_e32 v45, v45
	v_exp_f32_e32 v48, v48
	v_exp_f32_e32 v49, v49
	v_pk_mul_f32 v[44:45], v[46:47], v[44:45]
	v_add_f32_e32 v46, 1.0, v48
	v_add_f32_e32 v47, 1.0, v49
	v_mul_f32_e32 v48, 0xbfb8aa3b, v42
	v_mul_f32_e32 v49, 0xbfb8aa3b, v43
	v_exp_f32_e32 v48, v48
	v_exp_f32_e32 v49, v49
	v_rcp_f32_e32 v46, v46
	v_rcp_f32_e32 v47, v47
	v_add_f32_e32 v48, 1.0, v48
	v_add_f32_e32 v49, 1.0, v49
	v_rcp_f32_e32 v48, v48
	v_rcp_f32_e32 v49, v49
	v_pk_mul_f32 v[40:41], v[40:41], v[46:47]
	v_pk_mul_f32 v[38:39], v[44:45], v[38:39]
	v_pk_mul_f32 v[40:41], v[40:41], v[32:33]
	v_pk_mul_f32 v[32:33], v[42:43], v[48:49]
	v_lshl_add_u64 v[44:45], v[50:51], 0, v[112:113]
	v_pk_mul_f32 v[42:43], v[32:33], v[34:35]
	v_cvt_pk_bf16_f32 v32, v36, v37
	v_mul_f32_e32 v36, 0xbfb8aa3b, v28
	v_mul_f32_e32 v37, 0xbfb8aa3b, v29
	v_exp_f32_e32 v36, v36
	v_exp_f32_e32 v37, v37
	v_cvt_pk_bf16_f32 v33, v38, v39
	v_cvt_pk_bf16_f32 v34, v40, v41
	v_cvt_pk_bf16_f32 v35, v42, v43
	global_store_dwordx4 v[44:45], v[32:35], off
	s_nop 1
	v_add_f32_e32 v32, 1.0, v36
	v_add_f32_e32 v33, 1.0, v37
	v_rcp_f32_e32 v32, v32
	v_rcp_f32_e32 v33, v33
	v_add_u32_e32 v34, 0xa0, v152
	v_mad_i64_i32 v[34:35], s[22:23], v34, s45, v[144:145]
	v_pk_mul_f32 v[28:29], v[28:29], v[32:33]
	v_mul_f32_e32 v32, 0xbfb8aa3b, v30
	v_mul_f32_e32 v33, 0xbfb8aa3b, v31
	v_exp_f32_e32 v32, v32
	v_exp_f32_e32 v33, v33
	v_pk_mul_f32 v[20:21], v[28:29], v[20:21]
	v_add_f32_e32 v28, 1.0, v32
	v_add_f32_e32 v29, 1.0, v33
	v_mul_f32_e32 v32, 0xbfb8aa3b, v24
	v_mul_f32_e32 v33, 0xbfb8aa3b, v25
	v_rcp_f32_e32 v28, v28
	v_rcp_f32_e32 v29, v29
	v_exp_f32_e32 v32, v32
	v_exp_f32_e32 v33, v33
	v_pk_mul_f32 v[28:29], v[30:31], v[28:29]
	v_add_f32_e32 v30, 1.0, v32
	v_add_f32_e32 v31, 1.0, v33
	v_mul_f32_e32 v32, 0xbfb8aa3b, v26
	v_mul_f32_e32 v33, 0xbfb8aa3b, v27
	v_exp_f32_e32 v32, v32
	v_exp_f32_e32 v33, v33
	v_rcp_f32_e32 v30, v30
	v_rcp_f32_e32 v31, v31
	v_add_f32_e32 v32, 1.0, v32
	v_add_f32_e32 v33, 1.0, v33
	v_rcp_f32_e32 v32, v32
	v_rcp_f32_e32 v33, v33
	v_pk_mul_f32 v[24:25], v[24:25], v[30:31]
	v_pk_mul_f32 v[22:23], v[28:29], v[22:23]
	v_pk_mul_f32 v[24:25], v[24:25], v[16:17]
	v_pk_mul_f32 v[16:17], v[26:27], v[32:33]
	v_lshl_add_u64 v[28:29], v[34:35], 0, v[112:113]
	v_pk_mul_f32 v[26:27], v[16:17], v[18:19]
	v_cvt_pk_bf16_f32 v16, v20, v21
	v_mul_f32_e32 v20, 0xbfb8aa3b, v12
	v_mul_f32_e32 v21, 0xbfb8aa3b, v13
	v_exp_f32_e32 v20, v20
	v_exp_f32_e32 v21, v21
	v_cvt_pk_bf16_f32 v17, v22, v23
	v_cvt_pk_bf16_f32 v18, v24, v25
	v_cvt_pk_bf16_f32 v19, v26, v27
	global_store_dwordx4 v[28:29], v[16:19], off
	s_nop 1
	v_add_f32_e32 v16, 1.0, v20
	v_add_f32_e32 v17, 1.0, v21
	v_rcp_f32_e32 v16, v16
	v_rcp_f32_e32 v17, v17
	v_add_u32_e32 v18, 0xb0, v152
	v_mad_i64_i32 v[18:19], s[22:23], v18, s45, v[144:145]
	v_pk_mul_f32 v[12:13], v[12:13], v[16:17]
	v_mul_f32_e32 v16, 0xbfb8aa3b, v14
	v_mul_f32_e32 v17, 0xbfb8aa3b, v15
	v_exp_f32_e32 v16, v16
	v_exp_f32_e32 v17, v17
	v_pk_mul_f32 v[4:5], v[12:13], v[4:5]
	v_add_f32_e32 v12, 1.0, v16
	v_add_f32_e32 v13, 1.0, v17
	v_mul_f32_e32 v16, 0xbfb8aa3b, v8
	v_mul_f32_e32 v17, 0xbfb8aa3b, v9
	v_rcp_f32_e32 v12, v12
	v_rcp_f32_e32 v13, v13
	v_exp_f32_e32 v16, v16
	v_exp_f32_e32 v17, v17
	v_pk_mul_f32 v[12:13], v[14:15], v[12:13]
	v_add_f32_e32 v14, 1.0, v16
	v_add_f32_e32 v15, 1.0, v17
	v_mul_f32_e32 v16, 0xbfb8aa3b, v10
	v_mul_f32_e32 v17, 0xbfb8aa3b, v11
	v_exp_f32_e32 v16, v16
	v_exp_f32_e32 v17, v17
	v_rcp_f32_e32 v14, v14
	v_rcp_f32_e32 v15, v15
	v_add_f32_e32 v16, 1.0, v16
	v_add_f32_e32 v17, 1.0, v17
	v_rcp_f32_e32 v16, v16
	v_rcp_f32_e32 v17, v17
	v_pk_mul_f32 v[8:9], v[8:9], v[14:15]
	v_pk_mul_f32 v[6:7], v[12:13], v[6:7]
	v_pk_mul_f32 v[8:9], v[8:9], v[0:1]
	v_pk_mul_f32 v[0:1], v[10:11], v[16:17]
	v_lshl_add_u64 v[12:13], v[18:19], 0, v[112:113]
	v_pk_mul_f32 v[10:11], v[0:1], v[2:3]
	v_cvt_pk_bf16_f32 v0, v4, v5
	v_cvt_pk_bf16_f32 v1, v6, v7
	v_cvt_pk_bf16_f32 v2, v8, v9
	v_cvt_pk_bf16_f32 v3, v10, v11
	global_store_dwordx4 v[12:13], v[0:3], off
	s_cbranch_vccnz .LBB0_274
	s_andn2_b64 vcc, exec, s[0:1]
	s_cbranch_vccnz .LBB0_273
	s_branch .LBB0_273

.LBB0_1331:
	ds_read_b128 v[152:155], v149
	ds_read_b128 v[156:159], v149 offset:1024
	ds_read_b128 v[160:163], v149 offset:2048
	ds_read_b128 v[164:167], v149 offset:3072
	ds_read_b128 v[168:171], v150
	ds_read_b128 v[172:175], v150 offset:1024
	ds_read_b128 v[176:179], v150 offset:2048
	ds_read_b128 v[180:183], v150 offset:3072
	s_add_u32 s26, s24, 0xfffc0080
	s_addc_u32 s27, s25, -1
	s_cmp_eq_u32 s52, 12
	s_cselect_b32 s29, s17, s27
	s_cselect_b32 s28, s48, s26
	s_cselect_b32 s27, s15, s51
	s_cselect_b32 s26, s49, s50
	v_lshl_add_u64 v[144:145], s[24:25], 0, v[136:137]
	s_add_i32 m0, s23, 0xc000
	ds_read_b128 v[184:187], v151
	ds_read_b128 v[188:191], v151 offset:1024
	ds_read_b128 v[192:195], v151 offset:2048
	ds_read_b128 v[196:199], v151 offset:3072
	ds_read_b128 v[200:203], v151 offset:4096
	ds_read_b128 v[204:207], v151 offset:5120
	ds_read_b128 v[208:211], v151 offset:6144
	ds_read_b128 v[212:215], v151 offset:7168
	global_load_lds_dwordx4 v[144:145], off
	v_lshl_add_u64 v[144:145], s[24:25], 0, v[138:139]
	s_add_i32 m0, s23, 0xe000
	s_nop 0
	global_load_lds_dwordx4 v[144:145], off
	s_waitcnt vmcnt(8)
	s_waitcnt lgkmcnt(0)
	s_barrier
	s_setprio 1
	s_waitcnt lgkmcnt(0)
	v_mfma_f32_16x16x32_bf16 v[124:127], v[152:155], v[184:187], v[124:127]
	v_mfma_f32_16x16x32_bf16 v[120:123], v[160:163], v[184:187], v[120:123]
	v_mfma_f32_16x16x32_bf16 v[108:111], v[152:155], v[192:195], v[108:111]
	v_mfma_f32_16x16x32_bf16 v[104:107], v[160:163], v[192:195], v[104:107]
	v_mfma_f32_16x16x32_bf16 v[92:95], v[152:155], v[200:203], v[92:95]
	v_mfma_f32_16x16x32_bf16 v[88:91], v[160:163], v[200:203], v[88:91]
	v_mfma_f32_16x16x32_bf16 v[76:79], v[152:155], v[208:211], v[76:79]
	v_mfma_f32_16x16x32_bf16 v[72:75], v[160:163], v[208:211], v[72:75]
	v_mfma_f32_16x16x32_bf16 v[124:127], v[156:159], v[188:191], v[124:127]
	v_mfma_f32_16x16x32_bf16 v[120:123], v[164:167], v[188:191], v[120:123]
	v_mfma_f32_16x16x32_bf16 v[108:111], v[156:159], v[196:199], v[108:111]
	v_mfma_f32_16x16x32_bf16 v[104:107], v[164:167], v[196:199], v[104:107]
	v_mfma_f32_16x16x32_bf16 v[92:95], v[156:159], v[204:207], v[92:95]
	v_mfma_f32_16x16x32_bf16 v[88:91], v[164:167], v[204:207], v[88:91]
	v_mfma_f32_16x16x32_bf16 v[76:79], v[156:159], v[212:215], v[76:79]
	v_mfma_f32_16x16x32_bf16 v[72:75], v[164:167], v[212:215], v[72:75]
	s_setprio 0
	s_setprio 1
	v_mfma_f32_16x16x32_bf16 v[116:119], v[168:171], v[184:187], v[116:119]
	v_mfma_f32_16x16x32_bf16 v[112:115], v[176:179], v[184:187], v[112:115]
	v_mfma_f32_16x16x32_bf16 v[100:103], v[168:171], v[192:195], v[100:103]
	v_mfma_f32_16x16x32_bf16 v[96:99], v[176:179], v[192:195], v[96:99]
	v_mfma_f32_16x16x32_bf16 v[84:87], v[168:171], v[200:203], v[84:87]
	v_mfma_f32_16x16x32_bf16 v[80:83], v[176:179], v[200:203], v[80:83]
	v_mfma_f32_16x16x32_bf16 v[68:71], v[168:171], v[208:211], v[68:71]
	v_mfma_f32_16x16x32_bf16 v[64:67], v[176:179], v[208:211], v[64:67]
	v_mfma_f32_16x16x32_bf16 v[116:119], v[172:175], v[188:191], v[116:119]
	v_mfma_f32_16x16x32_bf16 v[112:115], v[180:183], v[188:191], v[112:115]
	v_mfma_f32_16x16x32_bf16 v[100:103], v[172:175], v[196:199], v[100:103]
	v_mfma_f32_16x16x32_bf16 v[96:99], v[180:183], v[196:199], v[96:99]
	v_mfma_f32_16x16x32_bf16 v[84:87], v[172:175], v[204:207], v[84:87]
	v_mfma_f32_16x16x32_bf16 v[80:83], v[180:183], v[204:207], v[80:83]
	v_mfma_f32_16x16x32_bf16 v[68:71], v[172:175], v[212:215], v[68:71]
	v_mfma_f32_16x16x32_bf16 v[64:67], v[180:183], v[212:215], v[64:67]
	s_setprio 0
	s_barrier
	s_add_i32 s53, s45, s34
	v_lshl_add_u64 v[144:145], s[26:27], 0, v[132:133]
	s_mov_b32 m0, s53
	ds_read_b128 v[184:187], v151 offset:16384
	ds_read_b128 v[188:191], v151 offset:17408
	ds_read_b128 v[192:195], v151 offset:18432
	ds_read_b128 v[196:199], v151 offset:19456
	ds_read_b128 v[200:203], v151 offset:20480
	ds_read_b128 v[204:207], v151 offset:21504
	ds_read_b128 v[208:211], v151 offset:22528
	ds_read_b128 v[212:215], v151 offset:23552
	global_load_lds_dwordx4 v[144:145], off
	s_add_i32 m0, s53, 0x2000
	s_add_u32 s54, s26, 0x40000
	v_lshl_add_u64 v[216:217], s[26:27], 0, v[128:129]
	s_addc_u32 s55, s27, 0
	s_add_i32 s53, s46, s34
	global_load_lds_dwordx4 v[216:217], off
	v_lshl_add_u64 v[218:219], s[54:55], 0, v[132:133]
	s_mov_b32 m0, s53
	v_lshl_add_u64 v[220:221], s[28:29], 0, v[130:131]
	global_load_lds_dwordx4 v[218:219], off
	v_lshl_add_u64 v[218:219], s[54:55], 0, v[128:129]
	s_add_i32 m0, s53, 0x2000
	s_nop 0
	global_load_lds_dwordx4 v[218:219], off
	v_lshl_add_u64 v[218:219], s[28:29], 0, v[134:135]
	s_mov_b32 m0, s23
	s_nop 0
	global_load_lds_dwordx4 v[218:219], off
	s_mov_b32 m0, s37
	s_nop 0
	global_load_lds_dwordx4 v[220:221], off
	s_waitcnt vmcnt(8)
	s_waitcnt lgkmcnt(0)
	s_barrier
	s_setprio 1
	s_waitcnt lgkmcnt(0)
	v_mfma_f32_16x16x32_bf16 v[60:63], v[152:155], v[184:187], v[60:63]
	v_mfma_f32_16x16x32_bf16 v[56:59], v[160:163], v[184:187], v[56:59]
	v_mfma_f32_16x16x32_bf16 v[44:47], v[152:155], v[192:195], v[44:47]
	v_mfma_f32_16x16x32_bf16 v[40:43], v[160:163], v[192:195], v[40:43]
	v_mfma_f32_16x16x32_bf16 v[28:31], v[152:155], v[200:203], v[28:31]
	v_mfma_f32_16x16x32_bf16 v[24:27], v[160:163], v[200:203], v[24:27]
	v_mfma_f32_16x16x32_bf16 v[12:15], v[152:155], v[208:211], v[12:15]
	v_mfma_f32_16x16x32_bf16 v[8:11], v[160:163], v[208:211], v[8:11]
	v_mfma_f32_16x16x32_bf16 v[60:63], v[156:159], v[188:191], v[60:63]
	v_mfma_f32_16x16x32_bf16 v[56:59], v[164:167], v[188:191], v[56:59]
	v_mfma_f32_16x16x32_bf16 v[44:47], v[156:159], v[196:199], v[44:47]
	v_mfma_f32_16x16x32_bf16 v[40:43], v[164:167], v[196:199], v[40:43]
	v_mfma_f32_16x16x32_bf16 v[28:31], v[156:159], v[204:207], v[28:31]
	v_mfma_f32_16x16x32_bf16 v[24:27], v[164:167], v[204:207], v[24:27]
	v_mfma_f32_16x16x32_bf16 v[12:15], v[156:159], v[212:215], v[12:15]
	v_mfma_f32_16x16x32_bf16 v[8:11], v[164:167], v[212:215], v[8:11]
	s_setprio 0
	s_setprio 1
	v_mfma_f32_16x16x32_bf16 v[52:55], v[168:171], v[184:187], v[52:55]
	v_mfma_f32_16x16x32_bf16 v[48:51], v[176:179], v[184:187], v[48:51]
	v_mfma_f32_16x16x32_bf16 v[36:39], v[168:171], v[192:195], v[36:39]
	v_mfma_f32_16x16x32_bf16 v[32:35], v[176:179], v[192:195], v[32:35]
	v_mfma_f32_16x16x32_bf16 v[20:23], v[168:171], v[200:203], v[20:23]
	v_mfma_f32_16x16x32_bf16 v[16:19], v[176:179], v[200:203], v[16:19]
	v_mfma_f32_16x16x32_bf16 v[4:7], v[168:171], v[208:211], v[4:7]
	v_mfma_f32_16x16x32_bf16 v[0:3], v[176:179], v[208:211], v[0:3]
	v_mfma_f32_16x16x32_bf16 v[52:55], v[172:175], v[188:191], v[52:55]
	v_mfma_f32_16x16x32_bf16 v[48:51], v[180:183], v[188:191], v[48:51]
	v_mfma_f32_16x16x32_bf16 v[36:39], v[172:175], v[196:199], v[36:39]
	v_mfma_f32_16x16x32_bf16 v[32:35], v[180:183], v[196:199], v[32:35]
	v_mfma_f32_16x16x32_bf16 v[20:23], v[172:175], v[204:207], v[20:23]
	v_mfma_f32_16x16x32_bf16 v[16:19], v[180:183], v[204:207], v[16:19]
	v_mfma_f32_16x16x32_bf16 v[4:7], v[172:175], v[212:215], v[4:7]
	v_mfma_f32_16x16x32_bf16 v[0:3], v[180:183], v[212:215], v[0:3]
	s_setprio 0
	s_barrier
	s_add_i32 s53, 0, 0x18000
	s_add_i32 s54, 0, 0x1c000
	v_add_u32_e32 v164, s53, v147
	v_add_u32_e32 v180, s54, v147
	ds_read_b128 v[152:155], v164
	ds_read_b128 v[156:159], v164 offset:1024
	ds_read_b128 v[160:163], v164 offset:2048
	ds_read_b128 v[164:167], v164 offset:3072
	ds_read_b128 v[168:171], v180
	ds_read_b128 v[172:175], v180 offset:1024
	ds_read_b128 v[176:179], v180 offset:2048
	ds_read_b128 v[180:183], v180 offset:3072
	s_add_u32 s28, s28, 0x40000
	s_addc_u32 s29, s29, 0
	s_mov_b32 m0, s38
	v_lshl_add_u64 v[222:223], s[28:29], 0, v[134:135]
	ds_read_b128 v[184:187], v151 offset:32768
	ds_read_b128 v[188:191], v151 offset:33792
	ds_read_b128 v[192:195], v151 offset:34816
	ds_read_b128 v[196:199], v151 offset:35840
	ds_read_b128 v[200:203], v151 offset:36864
	ds_read_b128 v[204:207], v151 offset:37888
	ds_read_b128 v[208:211], v151 offset:38912
	ds_read_b128 v[212:215], v151 offset:39936
	global_load_lds_dwordx4 v[222:223], off
	v_lshl_add_u64 v[222:223], s[28:29], 0, v[130:131]
	s_mov_b32 m0, s39
	s_nop 0
	global_load_lds_dwordx4 v[222:223], off
	s_waitcnt vmcnt(8)
	s_waitcnt lgkmcnt(0)
	s_barrier
	s_setprio 1
	s_waitcnt lgkmcnt(0)
	v_mfma_f32_16x16x32_bf16 v[124:127], v[152:155], v[184:187], v[124:127]
	v_mfma_f32_16x16x32_bf16 v[120:123], v[160:163], v[184:187], v[120:123]
	v_mfma_f32_16x16x32_bf16 v[108:111], v[152:155], v[192:195], v[108:111]
	v_mfma_f32_16x16x32_bf16 v[104:107], v[160:163], v[192:195], v[104:107]
	v_mfma_f32_16x16x32_bf16 v[92:95], v[152:155], v[200:203], v[92:95]
	v_mfma_f32_16x16x32_bf16 v[88:91], v[160:163], v[200:203], v[88:91]
	v_mfma_f32_16x16x32_bf16 v[76:79], v[152:155], v[208:211], v[76:79]
	v_mfma_f32_16x16x32_bf16 v[72:75], v[160:163], v[208:211], v[72:75]
	v_mfma_f32_16x16x32_bf16 v[124:127], v[156:159], v[188:191], v[124:127]
	v_mfma_f32_16x16x32_bf16 v[120:123], v[164:167], v[188:191], v[120:123]
	v_mfma_f32_16x16x32_bf16 v[108:111], v[156:159], v[196:199], v[108:111]
	v_mfma_f32_16x16x32_bf16 v[104:107], v[164:167], v[196:199], v[104:107]
	v_mfma_f32_16x16x32_bf16 v[92:95], v[156:159], v[204:207], v[92:95]
	v_mfma_f32_16x16x32_bf16 v[88:91], v[164:167], v[204:207], v[88:91]
	v_mfma_f32_16x16x32_bf16 v[76:79], v[156:159], v[212:215], v[76:79]
	v_mfma_f32_16x16x32_bf16 v[72:75], v[164:167], v[212:215], v[72:75]
	s_setprio 0
	s_setprio 1
	v_mfma_f32_16x16x32_bf16 v[116:119], v[168:171], v[184:187], v[116:119]
	v_mfma_f32_16x16x32_bf16 v[112:115], v[176:179], v[184:187], v[112:115]
	v_mfma_f32_16x16x32_bf16 v[100:103], v[168:171], v[192:195], v[100:103]
	v_mfma_f32_16x16x32_bf16 v[96:99], v[176:179], v[192:195], v[96:99]
	v_mfma_f32_16x16x32_bf16 v[84:87], v[168:171], v[200:203], v[84:87]
	v_mfma_f32_16x16x32_bf16 v[80:83], v[176:179], v[200:203], v[80:83]
	v_mfma_f32_16x16x32_bf16 v[68:71], v[168:171], v[208:211], v[68:71]
	v_mfma_f32_16x16x32_bf16 v[64:67], v[176:179], v[208:211], v[64:67]
	v_mfma_f32_16x16x32_bf16 v[116:119], v[172:175], v[188:191], v[116:119]
	v_mfma_f32_16x16x32_bf16 v[112:115], v[180:183], v[188:191], v[112:115]
	v_mfma_f32_16x16x32_bf16 v[100:103], v[172:175], v[196:199], v[100:103]
	v_mfma_f32_16x16x32_bf16 v[96:99], v[180:183], v[196:199], v[96:99]
	v_mfma_f32_16x16x32_bf16 v[84:87], v[172:175], v[204:207], v[84:87]
	v_mfma_f32_16x16x32_bf16 v[80:83], v[180:183], v[204:207], v[80:83]
	v_mfma_f32_16x16x32_bf16 v[68:71], v[172:175], v[212:215], v[68:71]
	v_mfma_f32_16x16x32_bf16 v[64:67], v[180:183], v[212:215], v[64:67]
	s_setprio 0
	s_barrier
	s_add_i32 s28, s53, s34
	v_lshl_add_u64 v[144:145], v[144:145], 0, s[10:11]
	s_mov_b32 m0, s28
	ds_read_b128 v[184:187], v151 offset:49152
	ds_read_b128 v[188:191], v151 offset:50176
	ds_read_b128 v[192:195], v151 offset:51200
	ds_read_b128 v[196:199], v151 offset:52224
	ds_read_b128 v[200:203], v151 offset:53248
	ds_read_b128 v[204:207], v151 offset:54272
	ds_read_b128 v[208:211], v151 offset:55296
	ds_read_b128 v[212:215], v151 offset:56320
	global_load_lds_dwordx4 v[144:145], off
	s_add_i32 m0, s28, 0x2000
	s_add_u32 s26, s26, 0x40080
	v_lshl_add_u64 v[144:145], v[216:217], 0, s[10:11]
	s_addc_u32 s27, s27, 0
	s_add_i32 s28, s54, s34
	global_load_lds_dwordx4 v[144:145], off
	v_lshl_add_u64 v[144:145], s[26:27], 0, v[132:133]
	s_mov_b32 m0, s28
	s_nop 0
	global_load_lds_dwordx4 v[144:145], off
	v_lshl_add_u64 v[144:145], s[26:27], 0, v[128:129]
	s_add_i32 m0, s28, 0x2000
	s_nop 0
	global_load_lds_dwordx4 v[144:145], off
	v_lshl_add_u64 v[144:145], v[218:219], 0, s[10:11]
	s_mov_b32 m0, s41
	s_nop 0
	global_load_lds_dwordx4 v[144:145], off
	v_lshl_add_u64 v[144:145], v[220:221], 0, s[10:11]
	s_mov_b32 m0, s42
	s_nop 0
	global_load_lds_dwordx4 v[144:145], off
	s_waitcnt vmcnt(8)
	s_waitcnt lgkmcnt(0)
	s_barrier
	s_setprio 1
	s_waitcnt lgkmcnt(0)
	v_mfma_f32_16x16x32_bf16 v[60:63], v[152:155], v[184:187], v[60:63]
	v_mfma_f32_16x16x32_bf16 v[56:59], v[160:163], v[184:187], v[56:59]
	v_mfma_f32_16x16x32_bf16 v[44:47], v[152:155], v[192:195], v[44:47]
	v_mfma_f32_16x16x32_bf16 v[40:43], v[160:163], v[192:195], v[40:43]
	v_mfma_f32_16x16x32_bf16 v[28:31], v[152:155], v[200:203], v[28:31]
	v_mfma_f32_16x16x32_bf16 v[24:27], v[160:163], v[200:203], v[24:27]
	v_mfma_f32_16x16x32_bf16 v[12:15], v[152:155], v[208:211], v[12:15]
	v_mfma_f32_16x16x32_bf16 v[8:11], v[160:163], v[208:211], v[8:11]
	v_mfma_f32_16x16x32_bf16 v[60:63], v[156:159], v[188:191], v[60:63]
	v_mfma_f32_16x16x32_bf16 v[56:59], v[164:167], v[188:191], v[56:59]
	v_mfma_f32_16x16x32_bf16 v[44:47], v[156:159], v[196:199], v[44:47]
	v_mfma_f32_16x16x32_bf16 v[40:43], v[164:167], v[196:199], v[40:43]
	v_mfma_f32_16x16x32_bf16 v[28:31], v[156:159], v[204:207], v[28:31]
	v_mfma_f32_16x16x32_bf16 v[24:27], v[164:167], v[204:207], v[24:27]
	v_mfma_f32_16x16x32_bf16 v[12:15], v[156:159], v[212:215], v[12:15]
	v_mfma_f32_16x16x32_bf16 v[8:11], v[164:167], v[212:215], v[8:11]
	s_setprio 0
	s_setprio 1
	v_mfma_f32_16x16x32_bf16 v[52:55], v[168:171], v[184:187], v[52:55]
	v_mfma_f32_16x16x32_bf16 v[48:51], v[176:179], v[184:187], v[48:51]
	v_mfma_f32_16x16x32_bf16 v[36:39], v[168:171], v[192:195], v[36:39]
	v_mfma_f32_16x16x32_bf16 v[32:35], v[176:179], v[192:195], v[32:35]
	v_mfma_f32_16x16x32_bf16 v[20:23], v[168:171], v[200:203], v[20:23]
	v_mfma_f32_16x16x32_bf16 v[16:19], v[176:179], v[200:203], v[16:19]
	v_mfma_f32_16x16x32_bf16 v[4:7], v[168:171], v[208:211], v[4:7]
	v_mfma_f32_16x16x32_bf16 v[0:3], v[176:179], v[208:211], v[0:3]
	v_mfma_f32_16x16x32_bf16 v[52:55], v[172:175], v[188:191], v[52:55]
	v_mfma_f32_16x16x32_bf16 v[48:51], v[180:183], v[188:191], v[48:51]
	v_mfma_f32_16x16x32_bf16 v[36:39], v[172:175], v[196:199], v[36:39]
	v_mfma_f32_16x16x32_bf16 v[32:35], v[180:183], v[196:199], v[32:35]
	v_mfma_f32_16x16x32_bf16 v[20:23], v[172:175], v[204:207], v[20:23]
	v_mfma_f32_16x16x32_bf16 v[16:19], v[180:183], v[204:207], v[16:19]
	v_mfma_f32_16x16x32_bf16 v[4:7], v[172:175], v[212:215], v[4:7]
	v_mfma_f32_16x16x32_bf16 v[0:3], v[180:183], v[212:215], v[0:3]
	s_setprio 0
	s_barrier
	s_add_i32 s52, s52, 2
	s_add_u32 s24, s24, 0x100
	s_addc_u32 s25, s25, 0
	s_add_u32 s50, s50, 0x100
	s_addc_u32 s51, s51, 0
	s_cmp_gt_u32 s52, 13
	s_cbranch_scc0 .LBB0_1331
	s_andn2_b64 vcc, s[12:13], s[6:7]
	s_and_b64 vcc, exec, vcc
	s_cbranch_vccz .LBB0_1334
	s_barrier
.LBB0_1334:
	v_mul_f32_e32 v144, 0xbfb8aa3b, v124
	v_exp_f32_e32 v144, v144
	v_mul_f32_e32 v145, 0xbfb8aa3b, v125
	v_exp_f32_e32 v145, v145
	v_mul_f32_e32 v153, 0xbfb8aa3b, v126
	v_add_f32_e32 v144, 1.0, v144
	v_rcp_f32_e32 v156, v144
	v_add_f32_e32 v144, 1.0, v145
	v_rcp_f32_e32 v157, v144
	v_exp_f32_e32 v153, v153
	v_lshl_or_b32 v154, s2, 7, v148
	v_lshl_add_u32 v152, s22, 8, v146
	v_pk_mul_f32 v[124:125], v[124:125], v[156:157]
	v_mul_f32_e32 v156, 0xbfb8aa3b, v127
	v_exp_f32_e32 v156, v156
	v_pk_mul_f32 v[116:117], v[124:125], v[116:117]
	v_add_f32_e32 v124, 1.0, v153
	v_mul_f32_e32 v153, 0xbfb8aa3b, v120
	v_add_f32_e32 v125, 1.0, v156
	v_rcp_f32_e32 v124, v124
	v_rcp_f32_e32 v125, v125
	v_exp_f32_e32 v153, v153
	v_mul_f32_e32 v156, 0xbfb8aa3b, v121
	v_exp_f32_e32 v156, v156
	v_pk_mul_f32 v[124:125], v[126:127], v[124:125]
	v_add_f32_e32 v126, 1.0, v153
	v_mul_f32_e32 v153, 0xbfb8aa3b, v122
	v_add_f32_e32 v127, 1.0, v156
	v_exp_f32_e32 v153, v153
	v_mul_f32_e32 v156, 0xbfb8aa3b, v123
	v_exp_f32_e32 v157, v156
	v_rcp_f32_e32 v126, v126
	v_add_f32_e32 v153, 1.0, v153
	v_rcp_f32_e32 v127, v127
	v_rcp_f32_e32 v156, v153
	v_add_f32_e32 v153, 1.0, v157
	v_rcp_f32_e32 v157, v153
	v_pk_mul_f32 v[120:121], v[120:121], v[126:127]
	v_pk_mul_f32 v[118:119], v[124:125], v[118:119]
	v_pk_mul_f32 v[120:121], v[120:121], v[112:113]
	v_pk_mul_f32 v[112:113], v[122:123], v[156:157]
	v_ashrrev_i32_e32 v155, 31, v154
	v_pk_mul_f32 v[122:123], v[112:113], v[114:115]
	v_cvt_pk_bf16_f32 v115, v118, v119
	v_mul_f32_e32 v118, 0xbfb8aa3b, v108
	v_mul_f32_e32 v119, 0xbfb8aa3b, v109
	v_exp_f32_e32 v118, v118
	v_exp_f32_e32 v119, v119
	v_mov_b64_e32 v[144:145], s[8:9]
	v_mad_i64_i32 v[158:159], s[24:25], v152, s47, v[144:145]
	v_lshlrev_b64 v[112:113], 1, v[154:155]
	v_lshl_add_u64 v[124:125], v[158:159], 0, v[112:113]
	v_cvt_pk_bf16_f32 v114, v116, v117
	v_cvt_pk_bf16_f32 v116, v120, v121
	v_cvt_pk_bf16_f32 v117, v122, v123
	global_store_dwordx4 v[124:125], v[114:117], off
	s_andn2_b64 vcc, exec, s[6:7]
	s_mov_b64 s[6:7], -1
	v_add_f32_e32 v114, 1.0, v118
	v_add_f32_e32 v115, 1.0, v119
	v_rcp_f32_e32 v114, v114
	v_rcp_f32_e32 v115, v115
	v_or_b32_e32 v116, 16, v152
	v_mad_i64_i32 v[116:117], s[24:25], v116, s47, v[144:145]
	v_pk_mul_f32 v[108:109], v[108:109], v[114:115]
	v_mul_f32_e32 v114, 0xbfb8aa3b, v110
	v_mul_f32_e32 v115, 0xbfb8aa3b, v111
	v_exp_f32_e32 v114, v114
	v_exp_f32_e32 v115, v115
	v_pk_mul_f32 v[100:101], v[108:109], v[100:101]
	v_add_f32_e32 v108, 1.0, v114
	v_add_f32_e32 v109, 1.0, v115
	v_mul_f32_e32 v114, 0xbfb8aa3b, v104
	v_mul_f32_e32 v115, 0xbfb8aa3b, v105
	v_rcp_f32_e32 v108, v108
	v_rcp_f32_e32 v109, v109
	v_exp_f32_e32 v114, v114
	v_exp_f32_e32 v115, v115
	v_pk_mul_f32 v[108:109], v[110:111], v[108:109]
	v_add_f32_e32 v110, 1.0, v114
	v_add_f32_e32 v111, 1.0, v115
	v_mul_f32_e32 v114, 0xbfb8aa3b, v106
	v_mul_f32_e32 v115, 0xbfb8aa3b, v107
	v_exp_f32_e32 v114, v114
	v_exp_f32_e32 v115, v115
	v_rcp_f32_e32 v110, v110
	v_rcp_f32_e32 v111, v111
	v_add_f32_e32 v114, 1.0, v114
	v_add_f32_e32 v115, 1.0, v115
	v_rcp_f32_e32 v114, v114
	v_rcp_f32_e32 v115, v115
	v_pk_mul_f32 v[104:105], v[104:105], v[110:111]
	v_pk_mul_f32 v[102:103], v[108:109], v[102:103]
	v_pk_mul_f32 v[104:105], v[104:105], v[96:97]
	v_pk_mul_f32 v[96:97], v[106:107], v[114:115]
	v_lshl_add_u64 v[108:109], v[116:117], 0, v[112:113]
	v_pk_mul_f32 v[106:107], v[96:97], v[98:99]
	v_cvt_pk_bf16_f32 v96, v100, v101
	v_mul_f32_e32 v100, 0xbfb8aa3b, v92
	v_mul_f32_e32 v101, 0xbfb8aa3b, v93
	v_exp_f32_e32 v100, v100
	v_exp_f32_e32 v101, v101
	v_cvt_pk_bf16_f32 v97, v102, v103
	v_cvt_pk_bf16_f32 v98, v104, v105
	v_cvt_pk_bf16_f32 v99, v106, v107
	global_store_dwordx4 v[108:109], v[96:99], off
	s_nop 1
	v_add_f32_e32 v96, 1.0, v100
	v_add_f32_e32 v97, 1.0, v101
	v_rcp_f32_e32 v96, v96
	v_rcp_f32_e32 v97, v97
	v_or_b32_e32 v98, 32, v152
	v_mad_i64_i32 v[98:99], s[24:25], v98, s47, v[144:145]
	v_pk_mul_f32 v[92:93], v[92:93], v[96:97]
	v_mul_f32_e32 v96, 0xbfb8aa3b, v94
	v_mul_f32_e32 v97, 0xbfb8aa3b, v95
	v_exp_f32_e32 v96, v96
	v_exp_f32_e32 v97, v97
	v_pk_mul_f32 v[84:85], v[92:93], v[84:85]
	v_add_f32_e32 v92, 1.0, v96
	v_add_f32_e32 v93, 1.0, v97
	v_mul_f32_e32 v96, 0xbfb8aa3b, v88
	v_mul_f32_e32 v97, 0xbfb8aa3b, v89
	v_rcp_f32_e32 v92, v92
	v_rcp_f32_e32 v93, v93
	v_exp_f32_e32 v96, v96
	v_exp_f32_e32 v97, v97
	v_pk_mul_f32 v[92:93], v[94:95], v[92:93]
	v_add_f32_e32 v94, 1.0, v96
	v_add_f32_e32 v95, 1.0, v97
	v_mul_f32_e32 v96, 0xbfb8aa3b, v90
	v_mul_f32_e32 v97, 0xbfb8aa3b, v91
	v_exp_f32_e32 v96, v96
	v_exp_f32_e32 v97, v97
	v_rcp_f32_e32 v94, v94
	v_rcp_f32_e32 v95, v95
	v_add_f32_e32 v96, 1.0, v96
	v_add_f32_e32 v97, 1.0, v97
	v_rcp_f32_e32 v96, v96
	v_rcp_f32_e32 v97, v97
	v_pk_mul_f32 v[88:89], v[88:89], v[94:95]
	v_pk_mul_f32 v[86:87], v[92:93], v[86:87]
	v_pk_mul_f32 v[88:89], v[88:89], v[80:81]
	v_pk_mul_f32 v[80:81], v[90:91], v[96:97]
	v_lshl_add_u64 v[92:93], v[98:99], 0, v[112:113]
	v_pk_mul_f32 v[90:91], v[80:81], v[82:83]
	v_cvt_pk_bf16_f32 v80, v84, v85
	v_mul_f32_e32 v84, 0xbfb8aa3b, v76
	v_mul_f32_e32 v85, 0xbfb8aa3b, v77
	v_exp_f32_e32 v84, v84
	v_exp_f32_e32 v85, v85
	v_cvt_pk_bf16_f32 v81, v86, v87
	v_cvt_pk_bf16_f32 v82, v88, v89
	v_cvt_pk_bf16_f32 v83, v90, v91
	global_store_dwordx4 v[92:93], v[80:83], off
	s_nop 1
	v_add_f32_e32 v80, 1.0, v84
	v_add_f32_e32 v81, 1.0, v85
	v_rcp_f32_e32 v80, v80
	v_rcp_f32_e32 v81, v81
	v_or_b32_e32 v82, 48, v152
	v_mad_i64_i32 v[82:83], s[24:25], v82, s47, v[144:145]
	v_pk_mul_f32 v[76:77], v[76:77], v[80:81]
	v_mul_f32_e32 v80, 0xbfb8aa3b, v78
	v_mul_f32_e32 v81, 0xbfb8aa3b, v79
	v_exp_f32_e32 v80, v80
	v_exp_f32_e32 v81, v81
	v_pk_mul_f32 v[68:69], v[76:77], v[68:69]
	v_add_f32_e32 v76, 1.0, v80
	v_add_f32_e32 v77, 1.0, v81
	v_mul_f32_e32 v80, 0xbfb8aa3b, v72
	v_mul_f32_e32 v81, 0xbfb8aa3b, v73
	v_rcp_f32_e32 v76, v76
	v_rcp_f32_e32 v77, v77
	v_exp_f32_e32 v80, v80
	v_exp_f32_e32 v81, v81
	v_pk_mul_f32 v[76:77], v[78:79], v[76:77]
	v_add_f32_e32 v78, 1.0, v80
	v_add_f32_e32 v79, 1.0, v81
	v_mul_f32_e32 v80, 0xbfb8aa3b, v74
	v_mul_f32_e32 v81, 0xbfb8aa3b, v75
	v_exp_f32_e32 v80, v80
	v_exp_f32_e32 v81, v81
	v_rcp_f32_e32 v78, v78
	v_rcp_f32_e32 v79, v79
	v_add_f32_e32 v80, 1.0, v80
	v_add_f32_e32 v81, 1.0, v81
	v_rcp_f32_e32 v80, v80
	v_rcp_f32_e32 v81, v81
	v_pk_mul_f32 v[72:73], v[72:73], v[78:79]
	v_pk_mul_f32 v[70:71], v[76:77], v[70:71]
	v_pk_mul_f32 v[72:73], v[72:73], v[64:65]
	v_pk_mul_f32 v[64:65], v[74:75], v[80:81]
	v_lshl_add_u64 v[76:77], v[82:83], 0, v[112:113]
	v_pk_mul_f32 v[74:75], v[64:65], v[66:67]
	v_cvt_pk_bf16_f32 v64, v68, v69
	v_mul_f32_e32 v68, 0xbfb8aa3b, v60
	v_mul_f32_e32 v69, 0xbfb8aa3b, v61
	v_exp_f32_e32 v68, v68
	v_exp_f32_e32 v69, v69
	v_cvt_pk_bf16_f32 v65, v70, v71
	v_cvt_pk_bf16_f32 v66, v72, v73
	v_cvt_pk_bf16_f32 v67, v74, v75
	global_store_dwordx4 v[76:77], v[64:67], off
	s_nop 1
	v_add_f32_e32 v64, 1.0, v68
	v_add_f32_e32 v65, 1.0, v69
	v_rcp_f32_e32 v64, v64
	v_rcp_f32_e32 v65, v65
	v_add_u32_e32 v66, 0x80, v152
	v_mad_i64_i32 v[66:67], s[24:25], v66, s47, v[144:145]
	v_pk_mul_f32 v[60:61], v[60:61], v[64:65]
	v_mul_f32_e32 v64, 0xbfb8aa3b, v62
	v_mul_f32_e32 v65, 0xbfb8aa3b, v63
	v_exp_f32_e32 v64, v64
	v_exp_f32_e32 v65, v65
	v_pk_mul_f32 v[52:53], v[60:61], v[52:53]
	v_add_f32_e32 v60, 1.0, v64
	v_add_f32_e32 v61, 1.0, v65
	v_mul_f32_e32 v64, 0xbfb8aa3b, v56
	v_mul_f32_e32 v65, 0xbfb8aa3b, v57
	v_rcp_f32_e32 v60, v60
	v_rcp_f32_e32 v61, v61
	v_exp_f32_e32 v64, v64
	v_exp_f32_e32 v65, v65
	v_pk_mul_f32 v[60:61], v[62:63], v[60:61]
	v_add_f32_e32 v62, 1.0, v64
	v_add_f32_e32 v63, 1.0, v65
	v_mul_f32_e32 v64, 0xbfb8aa3b, v58
	v_mul_f32_e32 v65, 0xbfb8aa3b, v59
	v_exp_f32_e32 v64, v64
	v_exp_f32_e32 v65, v65
	v_rcp_f32_e32 v62, v62
	v_rcp_f32_e32 v63, v63
	v_add_f32_e32 v64, 1.0, v64
	v_add_f32_e32 v65, 1.0, v65
	v_rcp_f32_e32 v64, v64
	v_rcp_f32_e32 v65, v65
	v_pk_mul_f32 v[56:57], v[56:57], v[62:63]
	v_pk_mul_f32 v[54:55], v[60:61], v[54:55]
	v_pk_mul_f32 v[56:57], v[56:57], v[48:49]
	v_pk_mul_f32 v[48:49], v[58:59], v[64:65]
	v_lshl_add_u64 v[60:61], v[66:67], 0, v[112:113]
	v_pk_mul_f32 v[58:59], v[48:49], v[50:51]
	v_cvt_pk_bf16_f32 v48, v52, v53
	v_mul_f32_e32 v52, 0xbfb8aa3b, v44
	v_mul_f32_e32 v53, 0xbfb8aa3b, v45
	v_exp_f32_e32 v52, v52
	v_exp_f32_e32 v53, v53
	v_cvt_pk_bf16_f32 v49, v54, v55
	v_cvt_pk_bf16_f32 v50, v56, v57
	v_cvt_pk_bf16_f32 v51, v58, v59
	global_store_dwordx4 v[60:61], v[48:51], off
	s_nop 1
	v_add_f32_e32 v48, 1.0, v52
	v_add_f32_e32 v49, 1.0, v53
	v_rcp_f32_e32 v48, v48
	v_rcp_f32_e32 v49, v49
	v_add_u32_e32 v50, 0x90, v152
	v_mad_i64_i32 v[50:51], s[24:25], v50, s47, v[144:145]
	v_pk_mul_f32 v[44:45], v[44:45], v[48:49]
	v_mul_f32_e32 v48, 0xbfb8aa3b, v46
	v_mul_f32_e32 v49, 0xbfb8aa3b, v47
	v_exp_f32_e32 v48, v48
	v_exp_f32_e32 v49, v49
	v_pk_mul_f32 v[36:37], v[44:45], v[36:37]
	v_add_f32_e32 v44, 1.0, v48
	v_add_f32_e32 v45, 1.0, v49
	v_mul_f32_e32 v48, 0xbfb8aa3b, v40
	v_mul_f32_e32 v49, 0xbfb8aa3b, v41
	v_rcp_f32_e32 v44, v44
	v_rcp_f32_e32 v45, v45
	v_exp_f32_e32 v48, v48
	v_exp_f32_e32 v49, v49
	v_pk_mul_f32 v[44:45], v[46:47], v[44:45]
	v_add_f32_e32 v46, 1.0, v48
	v_add_f32_e32 v47, 1.0, v49
	v_mul_f32_e32 v48, 0xbfb8aa3b, v42
	v_mul_f32_e32 v49, 0xbfb8aa3b, v43
	v_exp_f32_e32 v48, v48
	v_exp_f32_e32 v49, v49
	v_rcp_f32_e32 v46, v46
	v_rcp_f32_e32 v47, v47
	v_add_f32_e32 v48, 1.0, v48
	v_add_f32_e32 v49, 1.0, v49
	v_rcp_f32_e32 v48, v48
	v_rcp_f32_e32 v49, v49
	v_pk_mul_f32 v[40:41], v[40:41], v[46:47]
	v_pk_mul_f32 v[38:39], v[44:45], v[38:39]
	v_pk_mul_f32 v[40:41], v[40:41], v[32:33]
	v_pk_mul_f32 v[32:33], v[42:43], v[48:49]
	v_lshl_add_u64 v[44:45], v[50:51], 0, v[112:113]
	v_pk_mul_f32 v[42:43], v[32:33], v[34:35]
	v_cvt_pk_bf16_f32 v32, v36, v37
	v_mul_f32_e32 v36, 0xbfb8aa3b, v28
	v_mul_f32_e32 v37, 0xbfb8aa3b, v29
	v_exp_f32_e32 v36, v36
	v_exp_f32_e32 v37, v37
	v_cvt_pk_bf16_f32 v33, v38, v39
	v_cvt_pk_bf16_f32 v34, v40, v41
	v_cvt_pk_bf16_f32 v35, v42, v43
	global_store_dwordx4 v[44:45], v[32:35], off
	s_nop 1
	v_add_f32_e32 v32, 1.0, v36
	v_add_f32_e32 v33, 1.0, v37
	v_rcp_f32_e32 v32, v32
	v_rcp_f32_e32 v33, v33
	v_add_u32_e32 v34, 0xa0, v152
	v_mad_i64_i32 v[34:35], s[24:25], v34, s47, v[144:145]
	v_pk_mul_f32 v[28:29], v[28:29], v[32:33]
	v_mul_f32_e32 v32, 0xbfb8aa3b, v30
	v_mul_f32_e32 v33, 0xbfb8aa3b, v31
	v_exp_f32_e32 v32, v32
	v_exp_f32_e32 v33, v33
	v_pk_mul_f32 v[20:21], v[28:29], v[20:21]
	v_add_f32_e32 v28, 1.0, v32
	v_add_f32_e32 v29, 1.0, v33
	v_mul_f32_e32 v32, 0xbfb8aa3b, v24
	v_mul_f32_e32 v33, 0xbfb8aa3b, v25
	v_rcp_f32_e32 v28, v28
	v_rcp_f32_e32 v29, v29
	v_exp_f32_e32 v32, v32
	v_exp_f32_e32 v33, v33
	v_pk_mul_f32 v[28:29], v[30:31], v[28:29]
	v_add_f32_e32 v30, 1.0, v32
	v_add_f32_e32 v31, 1.0, v33
	v_mul_f32_e32 v32, 0xbfb8aa3b, v26
	v_mul_f32_e32 v33, 0xbfb8aa3b, v27
	v_exp_f32_e32 v32, v32
	v_exp_f32_e32 v33, v33
	v_rcp_f32_e32 v30, v30
	v_rcp_f32_e32 v31, v31
	v_add_f32_e32 v32, 1.0, v32
	v_add_f32_e32 v33, 1.0, v33
	v_rcp_f32_e32 v32, v32
	v_rcp_f32_e32 v33, v33
	v_pk_mul_f32 v[24:25], v[24:25], v[30:31]
	v_pk_mul_f32 v[22:23], v[28:29], v[22:23]
	v_pk_mul_f32 v[24:25], v[24:25], v[16:17]
	v_pk_mul_f32 v[16:17], v[26:27], v[32:33]
	v_lshl_add_u64 v[28:29], v[34:35], 0, v[112:113]
	v_pk_mul_f32 v[26:27], v[16:17], v[18:19]
	v_cvt_pk_bf16_f32 v16, v20, v21
	v_mul_f32_e32 v20, 0xbfb8aa3b, v12
	v_mul_f32_e32 v21, 0xbfb8aa3b, v13
	v_exp_f32_e32 v20, v20
	v_exp_f32_e32 v21, v21
	v_cvt_pk_bf16_f32 v17, v22, v23
	v_cvt_pk_bf16_f32 v18, v24, v25
	v_cvt_pk_bf16_f32 v19, v26, v27
	global_store_dwordx4 v[28:29], v[16:19], off
	s_nop 1
	v_add_f32_e32 v16, 1.0, v20
	v_add_f32_e32 v17, 1.0, v21
	v_rcp_f32_e32 v16, v16
	v_rcp_f32_e32 v17, v17
	v_add_u32_e32 v18, 0xb0, v152
	v_mad_i64_i32 v[18:19], s[24:25], v18, s47, v[144:145]
	v_pk_mul_f32 v[12:13], v[12:13], v[16:17]
	v_mul_f32_e32 v16, 0xbfb8aa3b, v14
	v_mul_f32_e32 v17, 0xbfb8aa3b, v15
	v_exp_f32_e32 v16, v16
	v_exp_f32_e32 v17, v17
	v_pk_mul_f32 v[4:5], v[12:13], v[4:5]
	v_add_f32_e32 v12, 1.0, v16
	v_add_f32_e32 v13, 1.0, v17
	v_mul_f32_e32 v16, 0xbfb8aa3b, v8
	v_mul_f32_e32 v17, 0xbfb8aa3b, v9
	v_rcp_f32_e32 v12, v12
	v_rcp_f32_e32 v13, v13
	v_exp_f32_e32 v16, v16
	v_exp_f32_e32 v17, v17
	v_pk_mul_f32 v[12:13], v[14:15], v[12:13]
	v_add_f32_e32 v14, 1.0, v16
	v_add_f32_e32 v15, 1.0, v17
	v_mul_f32_e32 v16, 0xbfb8aa3b, v10
	v_mul_f32_e32 v17, 0xbfb8aa3b, v11
	v_exp_f32_e32 v16, v16
	v_exp_f32_e32 v17, v17
	v_rcp_f32_e32 v14, v14
	v_rcp_f32_e32 v15, v15
	v_add_f32_e32 v16, 1.0, v16
	v_add_f32_e32 v17, 1.0, v17
	v_rcp_f32_e32 v16, v16
	v_rcp_f32_e32 v17, v17
	v_pk_mul_f32 v[8:9], v[8:9], v[14:15]
	v_pk_mul_f32 v[6:7], v[12:13], v[6:7]
	v_pk_mul_f32 v[8:9], v[8:9], v[0:1]
	v_pk_mul_f32 v[0:1], v[10:11], v[16:17]
	v_lshl_add_u64 v[12:13], v[18:19], 0, v[112:113]
	v_pk_mul_f32 v[10:11], v[0:1], v[2:3]
	v_cvt_pk_bf16_f32 v0, v4, v5
	v_cvt_pk_bf16_f32 v1, v6, v7
	v_cvt_pk_bf16_f32 v2, v8, v9
	v_cvt_pk_bf16_f32 v3, v10, v11
	global_store_dwordx4 v[12:13], v[0:3], off
	s_cbranch_vccnz .LBB0_1327
	s_andn2_b64 vcc, exec, s[0:1]
	s_cbranch_vccnz .LBB0_1326
	s_branch .LBB0_1326
